# seam spin loops: s_sleep 1 removed (tighter polling cadence) on top of arrival-counter polling v25
# baseline (speedup 1.0000x reference)
; __global__ void __launch_bounds__(512, 2) hybrid_fwd(Args args) {
;     ...
;     if (lo < 0) cg::this_grid().sync();
.LBB0_11:
	s_nop 0
	global_load_dword v2, v1, s[6:7] offset:32 sc1
	s_waitcnt vmcnt(0)
	v_and_b32_e32 v2, 0xffff0000, v2
	v_cmp_ne_u32_e32 vcc, v2, v0
	s_or_b64 s[8:9], vcc, s[8:9]
	s_andn2_b64 exec, exec, s[8:9]
	s_cbranch_execnz .LBB0_11

; __device__ __forceinline__ unsigned xb_ld(unsigned* p)              { return __hip_atomic_load(p, __ATOMIC_RELAXED, __HIP_MEMORY_SCOPE_AGENT); }
; __device__ __forceinline__ void xcd_barrier_complete(unsigned* bar, unsigned x, unsigned& nloc, unsigned& nx) {
;     ...
;     for (;;) {
;         sum = 0u; cnt = 0u; mine = 0u;
; #pragma unroll
;         for (unsigned j = 0; j < 16; ++j) { const unsigned c = xb_ld(&bar[XB_XCNT(j)]); sum += c; cnt += (c > 0u) ? 1u : 0u; mine = (j == x) ? c : mine; }
;         if (sum == G) break;
;         __builtin_amdgcn_s_sleep(1);
;         if ((++sp & 255u) == 0u) { if (xb_ld(&bar[XB_TMO])) break; if (sp > XB_SPIN_CAP) { atomicAdd(&bar[XB_TMO], 1u); break; } }
;     }
.LBB0_134:
	global_load_dword v15, v16, s[12:13] sc1
	global_load_dword v0, v16, s[14:15] sc1
	global_load_dword v1, v16, s[16:17] sc1
	global_load_dword v2, v16, s[18:19] sc1
	global_load_dword v3, v16, s[20:21] sc1
	global_load_dword v4, v16, s[22:23] sc1
	global_load_dword v5, v16, s[24:25] sc1
	global_load_dword v6, v16, s[26:27] sc1
	global_load_dword v7, v16, s[28:29] sc1
	global_load_dword v8, v16, s[30:31] sc1
	global_load_dword v9, v16, s[34:35] sc1
	global_load_dword v10, v16, s[36:37] sc1
	global_load_dword v11, v16, s[38:39] sc1
	global_load_dword v12, v16, s[40:41] sc1
	global_load_dword v13, v16, s[42:43] sc1
	global_load_dword v14, v16, s[50:51] sc1
	s_mov_b64 s[52:53], -1
	s_mov_b64 s[54:55], -1
	s_waitcnt vmcnt(14)
	v_add_u32_e32 v17, v0, v15
	s_waitcnt vmcnt(13)
	v_add_u32_e32 v17, v17, v1
	s_waitcnt vmcnt(12)
	v_add_u32_e32 v17, v17, v2
	s_waitcnt vmcnt(11)
	v_add_u32_e32 v17, v17, v3
	s_waitcnt vmcnt(10)
	v_add_u32_e32 v17, v17, v4
	s_waitcnt vmcnt(9)
	v_add_u32_e32 v17, v17, v5
	s_waitcnt vmcnt(8)
	v_add_u32_e32 v17, v17, v6
	s_waitcnt vmcnt(7)
	v_add_u32_e32 v17, v17, v7
	s_waitcnt vmcnt(6)
	v_add_u32_e32 v17, v17, v8
	s_waitcnt vmcnt(5)
	v_add_u32_e32 v17, v17, v9
	s_waitcnt vmcnt(4)
	v_add_u32_e32 v17, v17, v10
	s_waitcnt vmcnt(3)
	v_add_u32_e32 v17, v17, v11
	s_waitcnt vmcnt(2)
	v_add_u32_e32 v17, v17, v12
	s_waitcnt vmcnt(1)
	v_add_u32_e32 v17, v17, v13
	s_waitcnt vmcnt(0)
	v_add_u32_e32 v17, v17, v14
	v_cmp_eq_u32_e32 vcc, s3, v17
	s_cbranch_vccnz .LBB0_133
	s_and_b32 s52, s58, 0xff
	s_cmp_eq_u32 s52, 0
	s_mov_b64 s[52:53], -1
	s_mov_b64 s[56:57], -1
	s_nop 0
	s_cbranch_scc0 .LBB0_138
	global_load_dword v17, v16, s[10:11] sc1
	s_waitcnt vmcnt(0)
	v_cmp_eq_u32_e32 vcc, 0, v17
	s_cbranch_vccnz .LBB0_140
	s_mov_b64 s[56:57], 0

; __device__ __forceinline__ unsigned xb_ld(unsigned* p)              { return __hip_atomic_load(p, __ATOMIC_RELAXED, __HIP_MEMORY_SCOPE_AGENT); }
; #define XB_SPIN(cond, bar) do { unsigned _sp = 0; while (cond) { __builtin_amdgcn_s_sleep(1); \
;     if ((++_sp & 255u) == 0u) { if (xb_ld(&(bar)[XB_TMO])) break; if (_sp > XB_SPIN_CAP) { atomicAdd(&(bar)[XB_TMO], 1u); break; } } } } while (0)
; __device__ __forceinline__ void xcd_barrier(const XcdBarrier& b) {
;     ...
;         } else {
;             XB_SPIN(xb_ld(&bar[XB_TOPGEN]) == gen, bar);
;             __builtin_amdgcn_fence(__ATOMIC_ACQUIRE, "agent");
.LBB0_152:
	s_and_b32 s26, s3, 0xff
	s_mov_b64 s[24:25], -1
	s_cmp_lg_u32 s26, 0
	s_mov_b64 s[28:29], -1
	s_nop 0
	s_cbranch_scc1 .LBB0_155
	global_load_dword v2, v0, s[16:17] sc1
	s_waitcnt vmcnt(0)
	v_cmp_eq_u32_e32 vcc, 0, v2
	s_cbranch_vccnz .LBB0_157
	s_mov_b64 s[28:29], 0
	s_mov_b64 s[26:27], -1

; __device__ __forceinline__ unsigned xb_ld(unsigned* p)              { return __hip_atomic_load(p, __ATOMIC_RELAXED, __HIP_MEMORY_SCOPE_AGENT); }
; #define XB_SPIN(cond, bar) do { unsigned _sp = 0; while (cond) { __builtin_amdgcn_s_sleep(1); \
;     if ((++_sp & 255u) == 0u) { if (xb_ld(&(bar)[XB_TMO])) break; if (_sp > XB_SPIN_CAP) { atomicAdd(&(bar)[XB_TMO], 1u); break; } } } } while (0)
; __device__ __forceinline__ void xcd_barrier(const XcdBarrier& b) {
;     ...
;             else XB_SPIN(xb_ld(&bar[XB_TOPGEN]) == tg, bar);
.LBB0_169:
	s_and_b32 s24, s3, 0xff
	s_cmp_lg_u32 s24, 0
	s_mov_b64 s[26:27], -1
	s_nop 0
	s_cbranch_scc1 .LBB0_172
	global_load_dword v1, v0, s[16:17] sc1
	s_waitcnt vmcnt(0)
	v_cmp_eq_u32_e32 vcc, 0, v1
	s_cbranch_vccnz .LBB0_174
	s_mov_b64 s[26:27], 0
	s_mov_b64 s[24:25], -1

; __device__ __forceinline__ unsigned xb_ld(unsigned* p)              { return __hip_atomic_load(p, __ATOMIC_RELAXED, __HIP_MEMORY_SCOPE_AGENT); }
; __device__ __forceinline__ void xcd_barrier_complete(unsigned* bar, unsigned x, unsigned& nloc, unsigned& nx) {
;     ...
;     for (;;) {
;         sum = 0u; cnt = 0u; mine = 0u;
; #pragma unroll
;         for (unsigned j = 0; j < 16; ++j) { const unsigned c = xb_ld(&bar[XB_XCNT(j)]); sum += c; cnt += (c > 0u) ? 1u : 0u; mine = (j == x) ? c : mine; }
;         if (sum == G) break;
;         __builtin_amdgcn_s_sleep(1);
;         if ((++sp & 255u) == 0u) { if (xb_ld(&bar[XB_TMO])) break; if (sp > XB_SPIN_CAP) { atomicAdd(&bar[XB_TMO], 1u); break; } }
;     }
.LBB0_989:
	global_load_dword v15, v16, s[12:13] sc1
	global_load_dword v0, v16, s[14:15] sc1
	global_load_dword v1, v16, s[16:17] sc1
	global_load_dword v2, v16, s[18:19] sc1
	global_load_dword v3, v16, s[20:21] sc1
	global_load_dword v4, v16, s[22:23] sc1
	global_load_dword v5, v16, s[24:25] sc1
	global_load_dword v6, v16, s[26:27] sc1
	global_load_dword v7, v16, s[28:29] sc1
	global_load_dword v8, v16, s[30:31] sc1
	global_load_dword v9, v16, s[34:35] sc1
	global_load_dword v10, v16, s[36:37] sc1
	global_load_dword v11, v16, s[38:39] sc1
	global_load_dword v12, v16, s[40:41] sc1
	global_load_dword v13, v16, s[42:43] sc1
	global_load_dword v14, v16, s[44:45] sc1
	s_mov_b64 s[46:47], -1
	s_mov_b64 s[50:51], -1
	s_waitcnt vmcnt(14)
	v_add_u32_e32 v17, v0, v15
	s_waitcnt vmcnt(13)
	v_add_u32_e32 v17, v17, v1
	s_waitcnt vmcnt(12)
	v_add_u32_e32 v17, v17, v2
	s_waitcnt vmcnt(11)
	v_add_u32_e32 v17, v17, v3
	s_waitcnt vmcnt(10)
	v_add_u32_e32 v17, v17, v4
	s_waitcnt vmcnt(9)
	v_add_u32_e32 v17, v17, v5
	s_waitcnt vmcnt(8)
	v_add_u32_e32 v17, v17, v6
	s_waitcnt vmcnt(7)
	v_add_u32_e32 v17, v17, v7
	s_waitcnt vmcnt(6)
	v_add_u32_e32 v17, v17, v8
	s_waitcnt vmcnt(5)
	v_add_u32_e32 v17, v17, v9
	s_waitcnt vmcnt(4)
	v_add_u32_e32 v17, v17, v10
	s_waitcnt vmcnt(3)
	v_add_u32_e32 v17, v17, v11
	s_waitcnt vmcnt(2)
	v_add_u32_e32 v17, v17, v12
	s_waitcnt vmcnt(1)
	v_add_u32_e32 v17, v17, v13
	s_waitcnt vmcnt(0)
	v_add_u32_e32 v17, v17, v14
	v_cmp_eq_u32_e32 vcc, s3, v17
	s_cbranch_vccnz .LBB0_988
	s_and_b32 s46, s54, 0xff
	s_cmp_eq_u32 s46, 0
	s_mov_b64 s[46:47], -1
	s_mov_b64 s[52:53], -1
	s_nop 0
	s_cbranch_scc0 .LBB0_993
	global_load_dword v17, v16, s[10:11] sc1
	s_waitcnt vmcnt(0)
	v_cmp_eq_u32_e32 vcc, 0, v17
	s_cbranch_vccnz .LBB0_995
	s_mov_b64 s[52:53], 0

; __device__ __forceinline__ unsigned xb_ld(unsigned* p)              { return __hip_atomic_load(p, __ATOMIC_RELAXED, __HIP_MEMORY_SCOPE_AGENT); }
; __device__ __forceinline__ void xcd_barrier_complete(unsigned* bar, unsigned x, unsigned& nloc, unsigned& nx) {
;     ...
;     for (;;) {
;         sum = 0u; cnt = 0u; mine = 0u;
; #pragma unroll
;         for (unsigned j = 0; j < 16; ++j) { const unsigned c = xb_ld(&bar[XB_XCNT(j)]); sum += c; cnt += (c > 0u) ? 1u : 0u; mine = (j == x) ? c : mine; }
;         if (sum == G) break;
;         __builtin_amdgcn_s_sleep(1);
;         if ((++sp & 255u) == 0u) { if (xb_ld(&bar[XB_TMO])) break; if (sp > XB_SPIN_CAP) { atomicAdd(&bar[XB_TMO], 1u); break; } }
;     }
.LBB0_1112:
	global_load_dword v15, v16, s[12:13] sc1
	global_load_dword v0, v16, s[14:15] sc1
	global_load_dword v1, v16, s[16:17] sc1
	global_load_dword v2, v16, s[18:19] sc1
	global_load_dword v3, v16, s[20:21] sc1
	global_load_dword v4, v16, s[22:23] sc1
	global_load_dword v5, v16, s[24:25] sc1
	global_load_dword v6, v16, s[26:27] sc1
	global_load_dword v7, v16, s[28:29] sc1
	global_load_dword v8, v16, s[30:31] sc1
	global_load_dword v9, v16, s[34:35] sc1
	global_load_dword v10, v16, s[36:37] sc1
	global_load_dword v11, v16, s[38:39] sc1
	global_load_dword v12, v16, s[40:41] sc1
	global_load_dword v13, v16, s[42:43] sc1
	global_load_dword v14, v16, s[44:45] sc1
	s_mov_b64 s[46:47], -1
	s_mov_b64 s[48:49], -1
	s_waitcnt vmcnt(14)
	v_add_u32_e32 v17, v0, v15
	s_waitcnt vmcnt(13)
	v_add_u32_e32 v17, v17, v1
	s_waitcnt vmcnt(12)
	v_add_u32_e32 v17, v17, v2
	s_waitcnt vmcnt(11)
	v_add_u32_e32 v17, v17, v3
	s_waitcnt vmcnt(10)
	v_add_u32_e32 v17, v17, v4
	s_waitcnt vmcnt(9)
	v_add_u32_e32 v17, v17, v5
	s_waitcnt vmcnt(8)
	v_add_u32_e32 v17, v17, v6
	s_waitcnt vmcnt(7)
	v_add_u32_e32 v17, v17, v7
	s_waitcnt vmcnt(6)
	v_add_u32_e32 v17, v17, v8
	s_waitcnt vmcnt(5)
	v_add_u32_e32 v17, v17, v9
	s_waitcnt vmcnt(4)
	v_add_u32_e32 v17, v17, v10
	s_waitcnt vmcnt(3)
	v_add_u32_e32 v17, v17, v11
	s_waitcnt vmcnt(2)
	v_add_u32_e32 v17, v17, v12
	s_waitcnt vmcnt(1)
	v_add_u32_e32 v17, v17, v13
	s_waitcnt vmcnt(0)
	v_add_u32_e32 v17, v17, v14
	v_cmp_eq_u32_e32 vcc, s3, v17
	s_cbranch_vccnz .LBB0_1111
	s_and_b32 s46, s52, 0xff
	s_cmp_eq_u32 s46, 0
	s_mov_b64 s[46:47], -1
	s_mov_b64 s[50:51], -1
	s_nop 0
	s_cbranch_scc0 .LBB0_1116
	global_load_dword v17, v16, s[10:11] sc1
	s_waitcnt vmcnt(0)
	v_cmp_eq_u32_e32 vcc, 0, v17
	s_cbranch_vccnz .LBB0_1118
	s_mov_b64 s[50:51], 0

; __device__ __forceinline__ unsigned xb_ld(unsigned* p)              { return __hip_atomic_load(p, __ATOMIC_RELAXED, __HIP_MEMORY_SCOPE_AGENT); }
; __device__ __forceinline__ void xcd_barrier_complete(unsigned* bar, unsigned x, unsigned& nloc, unsigned& nx) {
;     ...
;     for (;;) {
;         sum = 0u; cnt = 0u; mine = 0u;
; #pragma unroll
;         for (unsigned j = 0; j < 16; ++j) { const unsigned c = xb_ld(&bar[XB_XCNT(j)]); sum += c; cnt += (c > 0u) ? 1u : 0u; mine = (j == x) ? c : mine; }
;         if (sum == G) break;
;         __builtin_amdgcn_s_sleep(1);
;         if ((++sp & 255u) == 0u) { if (xb_ld(&bar[XB_TMO])) break; if (sp > XB_SPIN_CAP) { atomicAdd(&bar[XB_TMO], 1u); break; } }
;     }
.LBB0_1323:
	global_load_dword v15, v16, s[10:11] sc1
	global_load_dword v0, v16, s[12:13] sc1
	global_load_dword v1, v16, s[14:15] sc1
	global_load_dword v2, v16, s[16:17] sc1
	global_load_dword v3, v16, s[18:19] sc1
	global_load_dword v4, v16, s[20:21] sc1
	global_load_dword v5, v16, s[22:23] sc1
	global_load_dword v6, v16, s[24:25] sc1
	global_load_dword v7, v16, s[26:27] sc1
	global_load_dword v8, v16, s[28:29] sc1
	global_load_dword v9, v16, s[30:31] sc1
	global_load_dword v10, v16, s[34:35] sc1
	global_load_dword v11, v16, s[36:37] sc1
	global_load_dword v12, v16, s[38:39] sc1
	global_load_dword v13, v16, s[40:41] sc1
	global_load_dword v14, v16, s[42:43] sc1
	s_mov_b64 s[44:45], -1
	s_mov_b64 s[46:47], -1
	s_waitcnt vmcnt(14)
	v_add_u32_e32 v17, v0, v15
	s_waitcnt vmcnt(13)
	v_add_u32_e32 v17, v17, v1
	s_waitcnt vmcnt(12)
	v_add_u32_e32 v17, v17, v2
	s_waitcnt vmcnt(11)
	v_add_u32_e32 v17, v17, v3
	s_waitcnt vmcnt(10)
	v_add_u32_e32 v17, v17, v4
	s_waitcnt vmcnt(9)
	v_add_u32_e32 v17, v17, v5
	s_waitcnt vmcnt(8)
	v_add_u32_e32 v17, v17, v6
	s_waitcnt vmcnt(7)
	v_add_u32_e32 v17, v17, v7
	s_waitcnt vmcnt(6)
	v_add_u32_e32 v17, v17, v8
	s_waitcnt vmcnt(5)
	v_add_u32_e32 v17, v17, v9
	s_waitcnt vmcnt(4)
	v_add_u32_e32 v17, v17, v10
	s_waitcnt vmcnt(3)
	v_add_u32_e32 v17, v17, v11
	s_waitcnt vmcnt(2)
	v_add_u32_e32 v17, v17, v12
	s_waitcnt vmcnt(1)
	v_add_u32_e32 v17, v17, v13
	s_waitcnt vmcnt(0)
	v_add_u32_e32 v17, v17, v14
	v_cmp_eq_u32_e32 vcc, s3, v17
	s_cbranch_vccnz .LBB0_1322
	s_and_b32 s44, s50, 0xff
	s_cmp_eq_u32 s44, 0
	s_mov_b64 s[44:45], -1
	s_mov_b64 s[48:49], -1
	s_nop 0
	s_cbranch_scc0 .LBB0_1327
	global_load_dword v17, v16, s[4:5] sc1
	s_waitcnt vmcnt(0)
	v_cmp_eq_u32_e32 vcc, 0, v17
	s_cbranch_vccnz .LBB0_1329
	s_mov_b64 s[48:49], 0

; __device__ __forceinline__ unsigned xb_ld(unsigned* p)              { return __hip_atomic_load(p, __ATOMIC_RELAXED, __HIP_MEMORY_SCOPE_AGENT); }
; #define XB_SPIN(cond, bar) do { unsigned _sp = 0; while (cond) { __builtin_amdgcn_s_sleep(1); \
;     if ((++_sp & 255u) == 0u) { if (xb_ld(&(bar)[XB_TMO])) break; if (_sp > XB_SPIN_CAP) { atomicAdd(&(bar)[XB_TMO], 1u); break; } } } } while (0)
; __device__ __forceinline__ void xcd_barrier(const XcdBarrier& b) {
;     ...
;         } else {
;             XB_SPIN(xb_ld(&bar[XB_TOPGEN]) == gen, bar);
;             __builtin_amdgcn_fence(__ATOMIC_ACQUIRE, "agent");
.LBB0_1341:
	s_and_b32 s24, s3, 0xff
	s_mov_b64 s[22:23], -1
	s_cmp_lg_u32 s24, 0
	s_mov_b64 s[26:27], -1
	s_nop 0
	s_cbranch_scc1 .LBB0_1344
	global_load_dword v2, v0, s[14:15] sc1
	s_waitcnt vmcnt(0)
	v_cmp_eq_u32_e32 vcc, 0, v2
	s_cbranch_vccnz .LBB0_1346
	s_mov_b64 s[26:27], 0
	s_mov_b64 s[24:25], -1

; __device__ __forceinline__ unsigned xb_ld(unsigned* p)              { return __hip_atomic_load(p, __ATOMIC_RELAXED, __HIP_MEMORY_SCOPE_AGENT); }
; #define XB_SPIN(cond, bar) do { unsigned _sp = 0; while (cond) { __builtin_amdgcn_s_sleep(1); \
;     if ((++_sp & 255u) == 0u) { if (xb_ld(&(bar)[XB_TMO])) break; if (_sp > XB_SPIN_CAP) { atomicAdd(&(bar)[XB_TMO], 1u); break; } } } } while (0)
; __device__ __forceinline__ void xcd_barrier(const XcdBarrier& b) {
;     ...
;             else XB_SPIN(xb_ld(&bar[XB_TOPGEN]) == tg, bar);
.LBB0_1358:
	s_and_b32 s22, s3, 0xff
	s_cmp_lg_u32 s22, 0
	s_mov_b64 s[24:25], -1
	s_nop 0
	s_cbranch_scc1 .LBB0_1361
	global_load_dword v1, v0, s[14:15] sc1
	s_waitcnt vmcnt(0)
	v_cmp_eq_u32_e32 vcc, 0, v1
	s_cbranch_vccnz .LBB0_1363
	s_mov_b64 s[24:25], 0
	s_mov_b64 s[22:23], -1
